# v29 + nt on the single-touch z gate-row loads (fox, sb, NSA)
# speedup vs baseline: 1.0007x; 1.0007x over previous
; DI void sb_unit(const bf16* PR, bf16* MIX, char* sm, int b, int h, int qb) {
;     ...
;     const int q0 = 256 * qb; const size_t rb = (size_t)b * S;
;     const int t = q0 + 32 * wid + r32, wq0 = q0 + 32 * wid;
;     bf16x8 qr[5];
; #pragma unroll
;     for (int d0 = 0; d0 < 4; ++d0) qr[d0] = *(const bf16x8*)(PR + (rb + t) * NP + C_SQ + 64 * h + 16 * d0 + 8 * hi);
;     qr[4] = (bf16x8){0, 0, 0, 0, 0, 0, 0, 0};
;     const bf16* Kb = PR + rb * NP + C_SK + 64 * h; const bf16* Vb = PR + rb * NP + C_SV + 64 * h;
;     float R = 1.f; f32x16 o0, o1;
; #pragma unroll
;     for (int i = 0; i < 16; ++i) { o0[i] = 0.f; o1[i] = 0.f; }
;     unsigned z_ = 0u; asm volatile("" : "+v"(z_)); u32x4 kr, vr, ar = {z_, z_, z_, z_};
;     const int nt = 4 * qb + 4;
;     u32x4 zpre[4];
;     { const bf16* zrow0 = PR + (rb + wq0) * NP + C_SZ + 64 * h;
; #pragma unroll
;       for (int j = 0; j < 4; ++j) zpre[j] = *(const u32x4*)(zrow0 + (size_t)((lane >> 3) + 8 * j) * NP + 8 * (lane & 7)); }
;     { const int kt = nt - 1; kv_issue(Kb + (size_t)(64 * kt) * NP, Vb + (size_t)(64 * kt) * NP, NP, wid, lane, kr, vr); }
;     kv_commit(sm, tid, wid, lane, kr, vr, ar); __syncthreads();
.LBB0_316:
	s_and_b64 vcc, exec, s[2:3]
	s_cbranch_vccz .LBB0_374
	s_add_i32 s2, s25, 0xfd00
	s_and_b32 s3, s2, 0xffff
	s_mul_i32 s3, s3, 0xaaab
	s_lshr_b32 s22, s3, 23
	s_lshl_b32 s3, s22, 6
	s_add_i32 s2, s2, s3
	s_and_b32 s3, s2, 0xff
	s_mulk_i32 s3, 0xab
	s_bfe_u32 s3, s3, 0x6000a
	v_mov_b32_e32 v149, v172
	s_mul_i32 s4, s3, 6
	s_sub_i32 s14, 7, s22
	v_readfirstlane_b32 s19, v149
	s_sub_i32 s2, s2, s4
	s_ashr_i32 s12, s19, 6
	s_lshl_b32 s6, s14, 8
	s_lshl_b32 s23, s12, 5
	s_and_b32 s2, s2, 0xff
	s_lshl_b32 s4, s3, 11
	s_add_i32 s13, s23, s6
	s_lshl_b32 s18, s2, 6
	s_lshl_b32 s8, s2, 7
	s_lshl_b32 s2, s3, 24
	v_and_b32_e32 v2, 31, v149
	s_add_u32 s2, s86, s2
	v_or_b32_e32 v4, s13, v2
	s_addc_u32 s3, s87, 0
	s_mov_b32 s5, s80
	v_ashrrev_i32_e32 v5, 31, v4
	s_add_u32 s2, s2, s8
	v_lshl_add_u64 v[4:5], s[4:5], 0, v[4:5]
	s_addc_u32 s3, s3, 0
	s_lshl_b32 s20, s14, 2
	s_ashr_i32 s5, s13, 31
	s_add_u32 s6, s4, s13
	s_addc_u32 s7, 0, s5
	s_lshl_b64 s[4:5], s[6:7], 13
	v_lshlrev_b64 v[4:5], 13, v[4:5]
	s_add_u32 s4, s86, s4
	v_bfe_u32 v163, v149, 5, 1
	v_lshl_add_u64 v[4:5], s[86:87], 0, v[4:5]
	s_mov_b32 s9, s80
	s_addc_u32 s5, s87, s5
	v_lshl_add_u64 v[4:5], v[4:5], 0, s[8:9]
	v_lshlrev_b32_e32 v0, 4, v163
	s_add_u32 s4, s4, s8
	v_lshlrev_b32_e32 v164, 4, v149
	v_lshl_add_u64 v[4:5], v[4:5], 0, v[0:1]
	s_addc_u32 s5, s5, 0
	v_and_b32_e32 v0, 0x70, v164
	global_load_dwordx4 v[96:99], v[4:5], off offset:3072
	global_load_dwordx4 v[100:103], v[4:5], off offset:3104
	global_load_dwordx4 v[104:107], v[4:5], off offset:3136
	global_load_dwordx4 v[108:111], v[4:5], off offset:3168
	v_lshl_add_u64 v[4:5], s[4:5], 0, v[0:1]
	v_lshlrev_b32_e32 v0, 10, v149
	v_and_b32_e32 v0, 0xe000, v0
	v_lshl_add_u64 v[4:5], v[4:5], 0, v[0:1]
	s_movk_i32 s4, 0x1000
	v_add_co_u32_e32 v6, vcc, s4, v4
	v_mov_b32_e32 v112, v1
	s_nop 0
	v_addc_co_u32_e32 v7, vcc, 0, v5, vcc
	s_mov_b32 s4, 0x11000
	global_load_dwordx4 v[92:95], v[6:7], off offset:1280 nt
	v_add_co_u32_e32 v6, vcc, s4, v4
	s_mov_b32 s4, 0x21000
	s_nop 0
	v_addc_co_u32_e32 v7, vcc, 0, v5, vcc
	global_load_dwordx4 v[88:91], v[6:7], off offset:1280 nt
	v_add_co_u32_e32 v6, vcc, s4, v4
	s_mov_b32 s4, 0x31000
	s_nop 0
	v_addc_co_u32_e32 v7, vcc, 0, v5, vcc
	v_add_co_u32_e32 v4, vcc, s4, v4
	s_add_u32 s4, s2, 0x1200
	s_addc_u32 s5, s3, 0
	s_lshl_b32 s8, s14, 20
	s_or_b32 s8, s8, 0xc0000
	s_lshl_b64 s[8:9], s[8:9], 1
	s_add_u32 s14, s2, s8
	v_and_b32_e32 v162, 63, v149
	s_addc_u32 s15, s3, s9
	v_addc_co_u32_e32 v5, vcc, 0, v5, vcc
	s_add_u32 s8, s4, s8
	v_lshlrev_b32_e32 v0, 13, v162
	global_load_dwordx4 v[80:83], v[4:5], off offset:1280 nt
	s_addc_u32 s9, s5, s9
	v_lshl_add_u64 v[4:5], s[14:15], 0, v[0:1]
	s_lshl_b32 s14, s12, 3
	s_lshl_b32 s16, s12, 4
	v_bfe_u32 v0, v149, 2, 4
	s_ashr_i32 s15, s14, 31
	v_and_or_b32 v3, s16, 48, v0
	v_lshlrev_b32_e32 v8, 3, v149
	v_lshl_add_u64 v[4:5], s[14:15], 1, v[4:5]
	v_lshlrev_b32_e32 v0, 13, v3
	s_and_b32 s16, s14, 0xffffffe0
	global_load_dwordx4 v[116:119], v[4:5], off offset:3840
	v_lshl_add_u64 v[4:5], s[8:9], 0, v[0:1]
	s_ashr_i32 s17, s16, 31
	v_and_b32_e32 v165, 24, v8
	v_lshl_add_u64 v[4:5], s[16:17], 1, v[4:5]
	v_lshlrev_b32_e32 v0, 1, v165
	v_lshl_add_u64 v[4:5], v[4:5], 0, v[0:1]
	global_load_dwordx4 v[84:87], v[6:7], off offset:1280 nt
	global_load_dwordx4 v[120:123], v[4:5], off
	s_cmp_lt_u32 s19, 64
	v_mov_b32_e32 v113, v112
	v_mov_b32_e32 v114, v112
	v_mov_b32_e32 v115, v112
	v_add_u32_e32 v4, 0, v164
	s_cselect_b64 s[8:9], -1, 0
	s_cmp_gt_u32 s19, 63
	v_lshlrev_b32_e32 v166, 4, v162
	s_waitcnt vmcnt(2)
	ds_write_b128 v4, v[116:119]
	s_waitcnt vmcnt(0)
	ds_write_b128 v4, v[120:123] offset:9216
	s_cbranch_scc1 .LBB0_319
	v_add_u32_e32 v4, 0, v166
	ds_write_b128 v4, v[112:115] offset:8192

; DI void fox_unit(const bf16* PR, const float* AUX, const float* bfp, bf16* MIX, char* sm, int b, int h, int qb, bool do_cs) {
;     ...
;         if (!more_) {
; #pragma unroll
;             for (int j = 0; j < 4; ++j) zpre[j] = *(const u32x4*)(zrow0 + (size_t)((lane >> 3) + 8 * j) * NP + 8 * (lane & 7));
;         }
.LBB0_342:
	s_add_i32 s36, s33, 1
	s_cmp_lt_u32 s36, s31
	s_cselect_b64 s[20:21], -1, 0
	s_mov_b64 s[22:23], -1
	s_and_b64 vcc, exec, s[20:21]
	s_cbranch_vccnz .LBB0_344
	global_load_dwordx4 v[106:109], v[162:163], off nt
	global_load_dwordx4 v[102:105], v[164:165], off nt
	global_load_dwordx4 v[98:101], v[166:167], off nt
	global_load_dwordx4 v[86:89], v[168:169], off nt
	s_mov_b64 s[22:23], 0

; DI float bf2f(unsigned h) { return __uint_as_float(h << 16); }
; DI unsigned cvtpk(float lo, float hi) { f32x2_t v = {lo, hi}; bf16x2_t b = __builtin_convertvector(v, bf16x2_t); return __builtin_bit_cast(unsigned, b); }
; DI float silu_f(float z) { return z * sigm_f(z); }
; DI void write_out_z(const f32x16& o0, const f32x16& o1, float sc, const u32x4 (&zpre)[4], bf16* orow0, size_t opitch, float* st, int lane) {
;     const int q = lane & 31, hi = lane >> 5;
; #pragma unroll
;     for (int d0 = 0; d0 < 2; ++d0)
; #pragma unroll
;         for (int gq = 0; gq < 4; ++gq) {
;             const int ch = 8 * d0 + 2 * gq + hi; const f32x16& o = d0 ? o1 : o0;
;             *(f32x4*)(st + q * 64 + ((ch ^ (q & 15)) << 2)) = (f32x4){o[4 * gq] * sc, o[4 * gq + 1] * sc, o[4 * gq + 2] * sc, o[4 * gq + 3] * sc};
;         }
; #pragma unroll
;     for (int j = 0; j < 4; ++j) {
;         const int row = (lane >> 3) + 8 * j, c = lane & 7;
;         const f32x4 a = *(const f32x4*)(st + row * 64 + (((2 * c) ^ (row & 15)) << 2)), b = *(const f32x4*)(st + row * 64 + (((2 * c + 1) ^ (row & 15)) << 2));
;         const u32x4 zz = zpre[j];
;         u32x4 w;
;         w.x = cvtpk(a[0] * silu_f(bf2f(zz.x & 0xffffu)), a[1] * silu_f(bf2f(zz.x >> 16)));
;         w.y = cvtpk(a[2] * silu_f(bf2f(zz.y & 0xffffu)), a[3] * silu_f(bf2f(zz.y >> 16)));
;         w.z = cvtpk(b[0] * silu_f(bf2f(zz.z & 0xffffu)), b[1] * silu_f(bf2f(zz.z >> 16)));
;         w.w = cvtpk(b[2] * silu_f(bf2f(zz.w & 0xffffu)), b[3] * silu_f(bf2f(zz.w >> 16)));
;         *(u32x4*)(orow0 + (size_t)row * opitch + 8 * c) = w;
;     }
; }
; DI void fox_unit(const bf16* PR, const float* AUX, const float* bfp, bf16* MIX, char* sm, int b, int h, int qb, bool do_cs) {
;     ...
;     const float lt = l + __shfl_xor(l, 32);
;     write_out_z(o0, o1, lt > 0.f ? 1.f / lt : 0.f, zpre, MIX + (rb + wq0) * D + 64 * h, D, (float*)(sm + L_TACC) + wid * 2048, lane);
.LBB0_367:
	s_waitcnt vmcnt(0)
	ds_bpermute_b32 v0, v187, v236
	s_lshl_b64 s[2:3], s[6:7], 11
	s_add_u32 s2, s96, s2
	s_addc_u32 s3, s97, s3
	s_add_u32 s2, s2, s8
	s_waitcnt lgkmcnt(0)
	v_add_f32_e32 v0, v236, v0
	v_div_scale_f32 v34, s[4:5], v0, v0, 1.0
	v_rcp_f32_e32 v35, v34
	v_div_scale_f32 v36, vcc, 1.0, v0, 1.0
	s_addc_u32 s3, s3, s9
	v_fma_f32 v37, -v34, v35, 1.0
	v_fmac_f32_e32 v35, v37, v35
	v_mul_f32_e32 v37, v36, v35
	s_waitcnt vmcnt(4)
	v_fma_f32 v38, -v34, v37, v36
	v_fmac_f32_e32 v37, v38, v35
	v_fma_f32 v34, -v34, v37, v36
	v_div_fmas_f32 v34, v34, v35, v37
	v_div_fixup_f32 v34, v34, v0, 1.0
	v_cmp_lt_f32_e32 vcc, 0, v0
	s_lshl_b32 s4, s27, 13
	s_add_i32 s4, s4, 0
	v_cndmask_b32_e32 v0, 0, v34, vcc
	v_lshlrev_b32_e32 v34, 8, v171
	s_add_i32 s4, s4, 0x14000
	v_and_b32_e32 v34, 0x1f00, v34
	v_add_u32_e32 v34, s4, v34
	v_bitop3_b32 v36, v193, v170, 15 bitop3:0x78
	v_and_b32_e32 v35, 15, v170
	v_pk_mul_f32 v[18:19], v[18:19], v[0:1] op_sel_hi:[1,0]
	v_pk_mul_f32 v[20:21], v[20:21], v[0:1] op_sel_hi:[1,0]
	v_lshl_add_u32 v36, v36, 4, v34
	ds_write_b128 v36, v[18:21]
	v_pk_mul_f32 v[18:19], v[22:23], v[0:1] op_sel_hi:[1,0]
	v_bitop3_b32 v22, v193, v35, 2 bitop3:0x36
	v_pk_mul_f32 v[20:21], v[24:25], v[0:1] op_sel_hi:[1,0]
	v_lshl_add_u32 v22, v22, 4, v34
	ds_write_b128 v22, v[18:21]
	v_bitop3_b32 v22, v193, v35, 4 bitop3:0x36
	v_pk_mul_f32 v[18:19], v[26:27], v[0:1] op_sel_hi:[1,0]
	v_pk_mul_f32 v[20:21], v[28:29], v[0:1] op_sel_hi:[1,0]
	v_lshl_add_u32 v22, v22, 4, v34
	ds_write_b128 v22, v[18:21]
	v_bitop3_b32 v22, v193, v35, 6 bitop3:0x36
	v_pk_mul_f32 v[18:19], v[30:31], v[0:1] op_sel_hi:[1,0]
	v_pk_mul_f32 v[20:21], v[32:33], v[0:1] op_sel_hi:[1,0]
	v_lshl_add_u32 v22, v22, 4, v34
	ds_write_b128 v22, v[18:21]
	v_bitop3_b32 v18, v193, v35, 8 bitop3:0x36
	v_pk_mul_f32 v[2:3], v[2:3], v[0:1] op_sel_hi:[1,0]
	v_pk_mul_f32 v[4:5], v[4:5], v[0:1] op_sel_hi:[1,0]
	v_lshl_add_u32 v18, v18, 4, v34
	ds_write_b128 v18, v[2:5]
	v_pk_mul_f32 v[2:3], v[6:7], v[0:1] op_sel_hi:[1,0]
	v_bitop3_b32 v6, v193, v35, 10 bitop3:0x36
	v_pk_mul_f32 v[4:5], v[8:9], v[0:1] op_sel_hi:[1,0]
	v_lshl_add_u32 v6, v6, 4, v34
	ds_write_b128 v6, v[2:5]
	v_bitop3_b32 v6, v193, v35, 12 bitop3:0x36
	v_pk_mul_f32 v[2:3], v[10:11], v[0:1] op_sel_hi:[1,0]
	v_pk_mul_f32 v[4:5], v[12:13], v[0:1] op_sel_hi:[1,0]
	v_lshl_add_u32 v6, v6, 4, v34
	ds_write_b128 v6, v[2:5]
	v_pk_mul_f32 v[2:3], v[14:15], v[0:1] op_sel_hi:[1,0]
	v_pk_mul_f32 v[4:5], v[16:17], v[0:1] op_sel_hi:[1,0]
	v_bitop3_b32 v0, v193, v35, 14 bitop3:0x36
	v_lshl_add_u32 v0, v0, 4, v34
	ds_write_b128 v0, v[2:5]
	v_and_b32_e32 v0, 7, v170
	v_lshrrev_b32_e32 v20, 3, v171
	v_lshlrev_b32_e32 v21, 1, v0
	v_bitop3_b32 v5, v21, v20, 1 bitop3:0x36
	v_lshlrev_b32_e32 v12, 16, v106
	v_lshlrev_b32_e32 v24, 4, v5
	v_and_b32_e32 v13, 0xffff0000, v106
	v_mul_f32_e32 v5, 0xbfb8aa3b, v12
	v_exp_f32_e32 v14, v5
	v_mul_f32_e32 v5, 0xbfb8aa3b, v13
	v_lshlrev_b32_e32 v0, 4, v0
	v_xor_b32_e32 v4, v20, v21
	v_exp_f32_e32 v15, v5
	v_lshl_add_u64 v[2:3], s[2:3], 0, v[0:1]
	v_lshl_add_u32 v0, v20, 8, s4
	v_lshlrev_b32_e32 v23, 4, v4
	v_add_u32_e32 v4, v0, v23
	v_add_u32_e32 v0, v0, v24
	ds_read_b128 v[4:7], v4
	ds_read_b128 v[8:11], v0
	v_add_f32_e32 v0, 1.0, v14
	v_lshlrev_b32_e32 v16, 16, v107
	v_rcp_f32_e32 v14, v0
	v_add_f32_e32 v0, 1.0, v15
	v_and_b32_e32 v17, 0xffff0000, v107
	v_mul_f32_e32 v15, 0xbfb8aa3b, v16
	v_exp_f32_e32 v18, v15
	v_mul_f32_e32 v15, 0xbfb8aa3b, v17
	v_exp_f32_e32 v19, v15
	v_rcp_f32_e32 v15, v0
	v_add_f32_e32 v0, 1.0, v18
	v_rcp_f32_e32 v18, v0
	v_add_f32_e32 v0, 1.0, v19
	v_rcp_f32_e32 v19, v0
	v_pk_mul_f32 v[12:13], v[14:15], v[12:13]
	v_and_b32_e32 v15, 0xffff0000, v109
	s_waitcnt lgkmcnt(1)
	v_pk_mul_f32 v[4:5], v[12:13], v[4:5]
	v_pk_mul_f32 v[12:13], v[18:19], v[16:17]
	v_cvt_pk_bf16_f32 v4, v4, v5
	v_pk_mul_f32 v[6:7], v[12:13], v[6:7]
	v_lshlrev_b32_e32 v12, 16, v108
	v_and_b32_e32 v13, 0xffff0000, v108
	v_mul_f32_e32 v0, 0xbfb8aa3b, v12
	v_exp_f32_e32 v0, v0
	v_mul_f32_e32 v5, 0xbfb8aa3b, v13
	v_exp_f32_e32 v14, v5
	v_cvt_pk_bf16_f32 v5, v6, v7
	v_add_f32_e32 v0, 1.0, v0
	v_rcp_f32_e32 v6, v0
	v_add_f32_e32 v0, 1.0, v14
	v_lshlrev_b32_e32 v14, 16, v109
	v_mul_f32_e32 v7, 0xbfb8aa3b, v14
	v_exp_f32_e32 v16, v7
	v_mul_f32_e32 v7, 0xbfb8aa3b, v15
	v_exp_f32_e32 v17, v7
	v_rcp_f32_e32 v7, v0
	v_add_f32_e32 v0, 1.0, v16
	v_rcp_f32_e32 v16, v0
	v_add_f32_e32 v0, 1.0, v17
	v_rcp_f32_e32 v17, v0
	v_pk_mul_f32 v[6:7], v[6:7], v[12:13]
	v_lshlrev_b32_e32 v0, 11, v20
	s_waitcnt lgkmcnt(0)
	v_pk_mul_f32 v[6:7], v[6:7], v[8:9]
	v_pk_mul_f32 v[8:9], v[16:17], v[14:15]
	v_or_b32_e32 v22, 1, v21
	v_pk_mul_f32 v[8:9], v[8:9], v[10:11]
	v_cvt_pk_bf16_f32 v6, v6, v7
	v_cvt_pk_bf16_f32 v7, v8, v9
	v_lshl_add_u64 v[8:9], v[2:3], 0, v[0:1]
	v_or_b32_e32 v0, 8, v20
	global_store_dwordx4 v[8:9], v[4:7], off
	v_lshlrev_b32_e32 v12, 16, v102
	v_and_b32_e32 v13, 0xffff0000, v102
	v_lshl_add_u32 v4, v0, 8, s4
	v_bitop3_b32 v5, v20, v21, 8 bitop3:0x36
	v_bitop3_b32 v6, v20, v22, 8 bitop3:0x36
	v_lshl_add_u32 v5, v5, 4, v4
	v_lshl_add_u32 v8, v6, 4, v4
	v_mul_f32_e32 v4, 0xbfb8aa3b, v12
	v_exp_f32_e32 v14, v4
	v_mul_f32_e32 v4, 0xbfb8aa3b, v13
	v_lshlrev_b32_e32 v16, 16, v103
	v_and_b32_e32 v17, 0xffff0000, v103
	v_exp_f32_e32 v15, v4
	v_mul_f32_e32 v18, 0xbfb8aa3b, v16
	v_mul_f32_e32 v19, 0xbfb8aa3b, v17
	v_exp_f32_e32 v18, v18
	v_exp_f32_e32 v19, v19
	v_add_f32_e32 v14, 1.0, v14
	v_add_f32_e32 v15, 1.0, v15
	v_rcp_f32_e32 v14, v14
	v_rcp_f32_e32 v15, v15
	v_add_f32_e32 v18, 1.0, v18
	v_add_f32_e32 v19, 1.0, v19
	ds_read_b128 v[4:7], v5
	ds_read_b128 v[8:11], v8
	v_rcp_f32_e32 v18, v18
	v_rcp_f32_e32 v19, v19
	v_pk_mul_f32 v[12:13], v[14:15], v[12:13]
	v_lshlrev_b32_e32 v0, 11, v0
	s_waitcnt lgkmcnt(1)
; DI float bf2f(unsigned h) { return __uint_as_float(h << 16); }
; DI unsigned cvtpk(float lo, float hi) { f32x2_t v = {lo, hi}; bf16x2_t b = __builtin_convertvector(v, bf16x2_t); return __builtin_bit_cast(unsigned, b); }
; DI float silu_f(float z) { return z * sigm_f(z); }
; DI void write_out_z(const f32x16& o0, const f32x16& o1, float sc, const u32x4 (&zpre)[4], bf16* orow0, size_t opitch, float* st, int lane) {
;     ...
;     for (int j = 0; j < 4; ++j) {
;         const int row = (lane >> 3) + 8 * j, c = lane & 7;
;         const f32x4 a = *(const f32x4*)(st + row * 64 + (((2 * c) ^ (row & 15)) << 2)), b = *(const f32x4*)(st + row * 64 + (((2 * c + 1) ^ (row & 15)) << 2));
;         const u32x4 zz = zpre[j];
;         u32x4 w;
;         w.x = cvtpk(a[0] * silu_f(bf2f(zz.x & 0xffffu)), a[1] * silu_f(bf2f(zz.x >> 16)));
;         w.y = cvtpk(a[2] * silu_f(bf2f(zz.y & 0xffffu)), a[3] * silu_f(bf2f(zz.y >> 16)));
;         w.z = cvtpk(b[0] * silu_f(bf2f(zz.z & 0xffffu)), b[1] * silu_f(bf2f(zz.z >> 16)));
;         w.w = cvtpk(b[2] * silu_f(bf2f(zz.w & 0xffffu)), b[3] * silu_f(bf2f(zz.w >> 16)));
;         *(u32x4*)(orow0 + (size_t)row * opitch + 8 * c) = w;
;     }
	v_pk_mul_f32 v[4:5], v[12:13], v[4:5]
	v_pk_mul_f32 v[12:13], v[18:19], v[16:17]
	v_cvt_pk_bf16_f32 v4, v4, v5
	v_pk_mul_f32 v[6:7], v[12:13], v[6:7]
	v_lshlrev_b32_e32 v12, 16, v104
	v_and_b32_e32 v13, 0xffff0000, v104
	v_mul_f32_e32 v5, 0xbfb8aa3b, v12
	v_exp_f32_e32 v14, v5
	v_mul_f32_e32 v5, 0xbfb8aa3b, v13
	v_exp_f32_e32 v15, v5
	v_cvt_pk_bf16_f32 v5, v6, v7
	v_add_f32_e32 v6, 1.0, v14
	v_lshlrev_b32_e32 v14, 16, v105
	v_add_f32_e32 v7, 1.0, v15
	v_and_b32_e32 v15, 0xffff0000, v105
	v_mul_f32_e32 v16, 0xbfb8aa3b, v14
	v_mul_f32_e32 v17, 0xbfb8aa3b, v15
	v_exp_f32_e32 v16, v16
	v_exp_f32_e32 v17, v17
	v_rcp_f32_e32 v6, v6
	v_rcp_f32_e32 v7, v7
	v_add_f32_e32 v16, 1.0, v16
	v_add_f32_e32 v17, 1.0, v17
	v_rcp_f32_e32 v16, v16
	v_rcp_f32_e32 v17, v17
	v_pk_mul_f32 v[6:7], v[6:7], v[12:13]
	v_lshlrev_b32_e32 v12, 16, v98
	s_waitcnt lgkmcnt(0)
	v_pk_mul_f32 v[6:7], v[6:7], v[8:9]
	v_pk_mul_f32 v[8:9], v[16:17], v[14:15]
	v_cvt_pk_bf16_f32 v6, v6, v7
	v_pk_mul_f32 v[8:9], v[8:9], v[10:11]
	v_and_b32_e32 v13, 0xffff0000, v98
	v_cvt_pk_bf16_f32 v7, v8, v9
	v_lshl_add_u64 v[8:9], v[2:3], 0, v[0:1]
	v_or_b32_e32 v0, 16, v20
	global_store_dwordx4 v[8:9], v[4:7], off
	v_lshlrev_b32_e32 v16, 16, v99
	v_and_b32_e32 v17, 0xffff0000, v99
	v_lshl_add_u32 v4, v0, 8, s4
	v_add_u32_e32 v5, v4, v23
	v_add_u32_e32 v8, v4, v24
	v_mul_f32_e32 v4, 0xbfb8aa3b, v12
	v_exp_f32_e32 v14, v4
	v_mul_f32_e32 v4, 0xbfb8aa3b, v13
	v_exp_f32_e32 v15, v4
	v_mul_f32_e32 v18, 0xbfb8aa3b, v16
	v_mul_f32_e32 v19, 0xbfb8aa3b, v17
	v_exp_f32_e32 v18, v18
	v_exp_f32_e32 v19, v19
	v_add_f32_e32 v14, 1.0, v14
	v_add_f32_e32 v15, 1.0, v15
	v_rcp_f32_e32 v14, v14
	v_rcp_f32_e32 v15, v15
	v_add_f32_e32 v18, 1.0, v18
	v_add_f32_e32 v19, 1.0, v19
	ds_read_b128 v[4:7], v5
	ds_read_b128 v[8:11], v8
	v_rcp_f32_e32 v18, v18
	v_rcp_f32_e32 v19, v19
	v_pk_mul_f32 v[12:13], v[14:15], v[12:13]
	v_lshlrev_b32_e32 v0, 11, v0
	s_waitcnt lgkmcnt(1)
	v_pk_mul_f32 v[4:5], v[12:13], v[4:5]
	v_pk_mul_f32 v[12:13], v[18:19], v[16:17]
	v_cvt_pk_bf16_f32 v4, v4, v5
	v_pk_mul_f32 v[6:7], v[12:13], v[6:7]
	v_lshlrev_b32_e32 v12, 16, v100
	v_and_b32_e32 v13, 0xffff0000, v100
	v_mul_f32_e32 v5, 0xbfb8aa3b, v12
	v_exp_f32_e32 v14, v5
	v_mul_f32_e32 v5, 0xbfb8aa3b, v13
	v_exp_f32_e32 v15, v5
	v_cvt_pk_bf16_f32 v5, v6, v7
	v_add_f32_e32 v6, 1.0, v14
	v_lshlrev_b32_e32 v14, 16, v101
	v_add_f32_e32 v7, 1.0, v15
	v_and_b32_e32 v15, 0xffff0000, v101
	v_mul_f32_e32 v16, 0xbfb8aa3b, v14
	v_mul_f32_e32 v17, 0xbfb8aa3b, v15
	v_exp_f32_e32 v16, v16
	v_exp_f32_e32 v17, v17
	v_rcp_f32_e32 v6, v6
	v_rcp_f32_e32 v7, v7
	v_add_f32_e32 v16, 1.0, v16
	v_add_f32_e32 v17, 1.0, v17
	v_rcp_f32_e32 v16, v16
	v_rcp_f32_e32 v17, v17
	v_pk_mul_f32 v[6:7], v[6:7], v[12:13]
	v_lshlrev_b32_e32 v12, 16, v86
	s_waitcnt lgkmcnt(0)
	v_pk_mul_f32 v[6:7], v[6:7], v[8:9]
	v_pk_mul_f32 v[8:9], v[16:17], v[14:15]
	v_cvt_pk_bf16_f32 v6, v6, v7
	v_pk_mul_f32 v[8:9], v[8:9], v[10:11]
	v_and_b32_e32 v13, 0xffff0000, v86
	v_cvt_pk_bf16_f32 v7, v8, v9
	v_lshl_add_u64 v[8:9], v[2:3], 0, v[0:1]
	v_or_b32_e32 v0, 24, v20
	global_store_dwordx4 v[8:9], v[4:7], off
	v_lshlrev_b32_e32 v16, 16, v87
	v_and_b32_e32 v17, 0xffff0000, v87
	v_lshl_add_u32 v4, v0, 8, s4
	v_bitop3_b32 v5, v0, v21, 15 bitop3:0x6c
	v_bitop3_b32 v6, v0, v22, 15 bitop3:0x6c
	v_lshl_add_u32 v5, v5, 4, v4
	v_lshl_add_u32 v8, v6, 4, v4
	v_mul_f32_e32 v4, 0xbfb8aa3b, v12
	v_exp_f32_e32 v14, v4
	v_mul_f32_e32 v4, 0xbfb8aa3b, v13
	v_exp_f32_e32 v15, v4
	v_mul_f32_e32 v18, 0xbfb8aa3b, v16
	v_mul_f32_e32 v19, 0xbfb8aa3b, v17
	v_exp_f32_e32 v18, v18
	v_exp_f32_e32 v19, v19
	v_add_f32_e32 v14, 1.0, v14
	v_add_f32_e32 v15, 1.0, v15
	v_rcp_f32_e32 v14, v14
	v_rcp_f32_e32 v15, v15
	v_add_f32_e32 v18, 1.0, v18
	v_add_f32_e32 v19, 1.0, v19
	ds_read_b128 v[4:7], v5
	ds_read_b128 v[8:11], v8
	v_rcp_f32_e32 v18, v18
	v_rcp_f32_e32 v19, v19
	v_pk_mul_f32 v[12:13], v[14:15], v[12:13]
	v_lshlrev_b32_e32 v0, 11, v0
	s_waitcnt lgkmcnt(1)
	v_pk_mul_f32 v[4:5], v[12:13], v[4:5]
	v_pk_mul_f32 v[12:13], v[18:19], v[16:17]
	v_cvt_pk_bf16_f32 v4, v4, v5
	v_pk_mul_f32 v[6:7], v[12:13], v[6:7]
	v_lshlrev_b32_e32 v12, 16, v88
	v_and_b32_e32 v13, 0xffff0000, v88
	v_mul_f32_e32 v5, 0xbfb8aa3b, v12
	v_exp_f32_e32 v14, v5
	v_mul_f32_e32 v5, 0xbfb8aa3b, v13
	v_exp_f32_e32 v15, v5
	v_cvt_pk_bf16_f32 v5, v6, v7
	v_add_f32_e32 v6, 1.0, v14
	v_lshlrev_b32_e32 v14, 16, v89
	v_add_f32_e32 v7, 1.0, v15
	v_and_b32_e32 v15, 0xffff0000, v89
	v_mul_f32_e32 v16, 0xbfb8aa3b, v14
	v_mul_f32_e32 v17, 0xbfb8aa3b, v15
	v_exp_f32_e32 v16, v16
	v_exp_f32_e32 v17, v17
	v_rcp_f32_e32 v6, v6
	v_rcp_f32_e32 v7, v7
	v_add_f32_e32 v16, 1.0, v16
	v_add_f32_e32 v17, 1.0, v17
	v_rcp_f32_e32 v16, v16
	v_rcp_f32_e32 v17, v17
	v_pk_mul_f32 v[6:7], v[6:7], v[12:13]
	v_lshl_add_u64 v[2:3], v[2:3], 0, v[0:1]
	s_waitcnt lgkmcnt(0)
; #define LAS __attribute__((address_space(3)))
; DI float bf2f(unsigned h) { return __uint_as_float(h << 16); }
; DI unsigned cvtpk(float lo, float hi) { f32x2_t v = {lo, hi}; bf16x2_t b = __builtin_convertvector(v, bf16x2_t); return __builtin_bit_cast(unsigned, b); }
; DI float silu_f(float z) { return z * sigm_f(z); }
; DI void write_out_z(const f32x16& o0, const f32x16& o1, float sc, const u32x4 (&zpre)[4], bf16* orow0, size_t opitch, float* st, int lane) {
;     ...
;         w.x = cvtpk(a[0] * silu_f(bf2f(zz.x & 0xffffu)), a[1] * silu_f(bf2f(zz.x >> 16)));
;         w.y = cvtpk(a[2] * silu_f(bf2f(zz.y & 0xffffu)), a[3] * silu_f(bf2f(zz.y >> 16)));
;         w.z = cvtpk(b[0] * silu_f(bf2f(zz.z & 0xffffu)), b[1] * silu_f(bf2f(zz.z >> 16)));
;         w.w = cvtpk(b[2] * silu_f(bf2f(zz.w & 0xffffu)), b[3] * silu_f(bf2f(zz.w >> 16)));
;         *(u32x4*)(orow0 + (size_t)row * opitch + 8 * c) = w;
; DI void fox_unit(const bf16* PR, const float* AUX, const float* bfp, bf16* MIX, char* sm, int b, int h, int qb, bool do_cs) {
;     ...
;     const int t = q0 + 32 * wid + r32;
;     bf16x8 qr[5];
; #pragma unroll
;     for (int d0 = 0; d0 < 4; ++d0) qr[d0] = *(const bf16x8*)(PR + (rb + t) * NP + C_FQ + 64 * h + 16 * d0 + 8 * hi);
;     { const short one = hi ? (short)0 : (short)0x3F80; qr[4] = (bf16x8){one, one, one, 0, 0, 0, 0, 0}; }
;     const float cref = cbuf[q0];
;     const bf16* Kb = PR + rb * NP + C_FK + 64 * h; const bf16* Vb = PR + rb * NP + C_FV + 64 * h;
;     float m = MINIT, l = 0.f; f32x16 o0, o1;
; #pragma unroll
;     for (int i = 0; i < 16; ++i) { o0[i] = 0.f; o1[i] = 0.f; }
;     unsigned z_ = 0u; asm volatile("" : "+v"(z_)); u32x4 kr, vr, ar = {z_, z_, z_, z_};
;     const int wq0 = q0 + 32 * wid;
;     u32x4 zpre[4];
;     const bf16* zrow0 = PR + (rb + wq0) * NP + C_FZ + 64 * h;
;     float q1 = 0.f;
; #pragma unroll
;     for (int d0 = 0; d0 < 4; ++d0)
; #pragma unroll
;         for (int j = 0; j < 8; ++j) q1 += fabsf(bf2f((unsigned)(unsigned short)qr[d0][j]));
;     q1 += __shfl_xor(q1, 32);
;     volatile LAS unsigned* kmx = (volatile LAS unsigned*)(sm + L_MISC) + 32;
;     for (int it_ = -1, nt_ = (4 * qb + 4); it_ < nt_; ++it_) {
;         const bool more_ = it_ + 1 < nt_;
;         if (!more_) {
; #pragma unroll
;             for (int j = 0; j < 4; ++j) zpre[j] = *(const u32x4*)(zrow0 + (size_t)((lane >> 3) + 8 * j) * NP + 8 * (lane & 7));
	v_pk_mul_f32 v[6:7], v[6:7], v[8:9]
	v_pk_mul_f32 v[8:9], v[16:17], v[14:15]
	v_cvt_pk_bf16_f32 v6, v6, v7
	v_pk_mul_f32 v[8:9], v[8:9], v[10:11]
	v_mov_b32_e32 v193, v172
	v_cvt_pk_bf16_f32 v7, v8, v9
	global_store_dwordx4 v[2:3], v[4:7], off
	s_lshl_b32 s3, s13, 2
	v_readfirstlane_b32 s2, v193
	s_ashr_i32 s18, s2, 6
	s_lshl_b32 s26, s18, 5
	v_and_b32_e32 v12, 31, v193
	s_add_i32 s19, s26, s13
	v_or_b32_e32 v2, s19, v12
	v_ashrrev_i32_e32 v3, 31, v2
	v_lshl_add_u64 v[2:3], s[14:15], 0, v[2:3]
	v_lshlrev_b64 v[2:3], 13, v[2:3]
	v_bfe_u32 v194, v193, 5, 1
	v_lshl_add_u64 v[2:3], s[86:87], 0, v[2:3]
	v_lshl_add_u64 v[2:3], v[2:3], 0, s[8:9]
	v_lshlrev_b32_e32 v0, 4, v194
	v_lshl_add_u64 v[2:3], v[2:3], 0, v[0:1]
	global_load_dwordx4 v[84:87], v[2:3], off
	global_load_dwordx4 v[88:91], v[2:3], off offset:32
	global_load_dwordx4 v[92:95], v[2:3], off offset:64
	global_load_dwordx4 v[96:99], v[2:3], off offset:96
	s_add_i32 s3, s3, 0
	v_mov_b32_e32 v0, s3
	ds_read_b32 v35, v0 offset:36864
	s_ashr_i32 s3, s19, 31
	s_add_u32 s6, s14, s19
	s_addc_u32 s7, s15, s3
	v_and_b32_e32 v195, 63, v193
	v_mov_b32_e32 v2, v1
	s_cmpk_lt_i32 s25, 0xfe81
	s_waitcnt vmcnt(3)
	v_lshlrev_b32_e32 v0, 16, v84
	v_and_b32_e32 v3, 0xffff0000, v84
	v_add_f32_e64 v0, |v0|, |v3|
	v_lshlrev_b32_e32 v3, 16, v85
	v_add_f32_e64 v0, |v3|, v0
	v_and_b32_e32 v3, 0xffff0000, v85
	v_add_f32_e64 v0, |v3|, v0
	v_lshlrev_b32_e32 v3, 16, v86
	v_add_f32_e64 v0, |v3|, v0
	v_and_b32_e32 v3, 0xffff0000, v86
	v_add_f32_e64 v0, |v3|, v0
	v_lshlrev_b32_e32 v3, 16, v87
	v_add_f32_e64 v0, |v3|, v0
	v_and_b32_e32 v3, 0xffff0000, v87
	v_add_f32_e64 v0, |v3|, v0
	s_waitcnt vmcnt(2)
	v_lshlrev_b32_e32 v3, 16, v88
	v_add_f32_e64 v0, |v3|, v0
	v_and_b32_e32 v3, 0xffff0000, v88
	v_add_f32_e64 v0, |v3|, v0
	v_lshlrev_b32_e32 v3, 16, v89
	v_add_f32_e64 v0, |v3|, v0
	v_and_b32_e32 v3, 0xffff0000, v89
	v_add_f32_e64 v0, |v3|, v0
	v_lshlrev_b32_e32 v3, 16, v90
	v_add_f32_e64 v0, |v3|, v0
	v_and_b32_e32 v3, 0xffff0000, v90
	v_add_f32_e64 v0, |v3|, v0
	v_lshlrev_b32_e32 v3, 16, v91
	v_add_f32_e64 v0, |v3|, v0
	v_and_b32_e32 v3, 0xffff0000, v91
	v_add_f32_e64 v0, |v3|, v0
	s_waitcnt vmcnt(1)
	v_lshlrev_b32_e32 v3, 16, v92
	v_add_f32_e64 v0, |v3|, v0
	v_and_b32_e32 v3, 0xffff0000, v92
	v_add_f32_e64 v0, |v3|, v0
	v_lshlrev_b32_e32 v3, 16, v93
	v_add_f32_e64 v0, |v3|, v0
	v_and_b32_e32 v3, 0xffff0000, v93
	v_add_f32_e64 v0, |v3|, v0
	v_lshlrev_b32_e32 v3, 16, v94
	v_add_f32_e64 v0, |v3|, v0
	v_and_b32_e32 v3, 0xffff0000, v94
	v_add_f32_e64 v0, |v3|, v0
	v_lshlrev_b32_e32 v3, 16, v95
	v_add_f32_e64 v0, |v3|, v0
	v_and_b32_e32 v3, 0xffff0000, v95
	v_add_f32_e64 v0, |v3|, v0
	s_waitcnt vmcnt(0)
	v_lshlrev_b32_e32 v3, 16, v96
	v_add_f32_e64 v0, |v3|, v0
	v_and_b32_e32 v3, 0xffff0000, v96
	v_add_f32_e64 v0, |v3|, v0
	v_lshlrev_b32_e32 v3, 16, v97
	v_add_f32_e64 v0, |v3|, v0
	v_and_b32_e32 v3, 0xffff0000, v97
	v_add_f32_e64 v0, |v3|, v0
	v_lshlrev_b32_e32 v3, 16, v98
	v_add_f32_e64 v0, |v3|, v0
	v_and_b32_e32 v3, 0xffff0000, v98
	v_add_f32_e64 v0, |v3|, v0
	v_lshlrev_b32_e32 v3, 16, v99
	v_add_f32_e64 v0, |v3|, v0
	v_and_b32_e32 v3, 0xffff0000, v99
	v_add_f32_e64 v13, |v3|, v0
	ds_bpermute_b32 v14, v187, v13
	s_cbranch_scc1 .LBB0_376
	s_lshl_b64 s[4:5], s[6:7], 13
	s_add_u32 s3, s86, s4
	s_addc_u32 s5, s87, s5
	s_add_u32 s4, s3, s8
	s_addc_u32 s5, s5, s9
	s_cmp_lt_u32 s2, 64
	v_lshlrev_b32_e32 v0, 9, v195
	v_lshlrev_b32_e32 v196, 4, v193
	s_cselect_b64 s[2:3], -1, 0
	s_cmpk_gt_i32 s25, 0xff40
	v_and_b32_e32 v3, 0x7000, v0
	v_and_b32_e32 v0, 0x70, v196
	s_cselect_b64 s[14:15], -1, 0
	v_lshl_add_u64 v[8:9], s[4:5], 0, v[0:1]
	s_mov_b64 s[4:5], -1
	s_and_b64 vcc, exec, s[14:15]
	v_lshlrev_b32_e32 v10, 1, v3
	s_cbranch_vccnz .LBB0_370
	v_mov_b32_e32 v11, v1
	v_lshl_add_u64 v[4:5], v[8:9], 0, v[10:11]
	v_add_co_u32_e32 v6, vcc, 0x10000, v4
	s_mov_b64 s[4:5], 0
	s_nop 0
	v_addc_co_u32_e32 v7, vcc, 0, v5, vcc
	global_load_dwordx4 v[80:83], v[4:5], off offset:2304 nt
	global_load_dwordx4 v[76:79], v[6:7], off offset:2304 nt
	v_add_co_u32_e32 v6, vcc, 0x20000, v4
	s_nop 1
	v_addc_co_u32_e32 v7, vcc, 0, v5, vcc
	v_add_co_u32_e32 v4, vcc, 0x30000, v4
	s_nop 1
	v_addc_co_u32_e32 v5, vcc, 0, v5, vcc
	global_load_dwordx4 v[72:75], v[6:7], off offset:2304 nt
	global_load_dwordx4 v[68:71], v[4:5], off offset:2304 nt

; DI void fox_unit(const bf16* PR, const float* AUX, const float* bfp, bf16* MIX, char* sm, int b, int h, int qb, bool do_cs) {
;     ...
;     for (int it_ = -1, nt_ = (4 * qb + 4); it_ < nt_; ++it_) {
;         const bool more_ = it_ + 1 < nt_;
;         if (!more_) {
; #pragma unroll
;             for (int j = 0; j < 4; ++j) zpre[j] = *(const u32x4*)(zrow0 + (size_t)((lane >> 3) + 8 * j) * NP + 8 * (lane & 7));
;         }
.LBB0_386:
	s_add_i32 s25, s26, 1
	s_cmp_lt_i32 s25, s12
	s_cselect_b64 s[14:15], -1, 0
	s_mov_b64 s[16:17], -1
	s_and_b64 vcc, exec, s[14:15]
	s_cbranch_vccnz .LBB0_388
	global_load_dwordx4 v[80:83], v[164:165], off nt
	global_load_dwordx4 v[76:79], v[166:167], off nt
	global_load_dwordx4 v[72:75], v[168:169], off nt
	global_load_dwordx4 v[68:71], v[170:171], off nt
	s_mov_b64 s[16:17], 0

; DI void nsa_unit(const bf16* PR, const float* AUX, const bf16* KC, const bf16* VC, bf16* MIX, char* sm, int b, int qb) {
;     ...
;         for (int it_ = -1, nt_ = (cur - j0 + 1); it_ < nt_; ++it_) {
;         const bool more_ = it_ + 1 < nt_;
;         if (!more_) { const bf16* zrow0 = PR + (rb + 64 * qb + 32 * (wid & 1)) * NP + C_NZ + 64 * g;
; #pragma unroll
;             for (int j = 0; j < 2; ++j) zpre[j] = *(const u32x4*)(zrow0 + (size_t)((lane >> 3) + 8 * j) * NP + 8 * (lane & 7)); }
.LBB0_531:
	s_add_i32 s18, s17, 8
	s_cmp_lt_i32 s18, s12
	s_cselect_b64 s[6:7], -1, 0
	s_mov_b64 s[0:1], -1
	s_and_b64 vcc, exec, s[6:7]
	s_cbranch_vccnz .LBB0_533
	global_load_dwordx4 v[36:39], v[146:147], off nt
	global_load_dwordx4 v[40:43], v[158:159], off nt
	s_mov_b64 s[0:1], 0
